# logical workgroup id built from the hardware XCC id and the arrival rank on that XCC (so block-local placement holds by construction, not by dispatch order); a2 / y-partial stores plain L2 write-back
# baseline (speedup 1.0000x reference)
_Z10fwd_kernel6Params:
	s_add_u32 s10, s0, 0xa0
	v_writelane_b32 v255, s2, 0
	s_load_dwordx2 s[28:29], s[0:1], 0xa0
	s_load_dword s2, s[0:1], 0xa8
	s_addc_u32 s11, s1, 0
	v_and_b32_e32 v147, 0x3ff, v0
	v_cmp_eq_u32_e32 vcc, 0, v147
	s_and_saveexec_b64 s[4:5], vcc
	s_cbranch_execz .LBB0_3
	s_add_i32 s3, 0, 0x23f00
	v_mov_b32_e32 v1, 0
	v_mov_b32_e32 v2, s3
	s_add_i32 s3, 0, 0x23f04
	s_mov_b64 s[6:7], exec
	ds_write_b32 v2, v1
	v_mov_b32_e32 v2, s3
	ds_write_b32 v2, v1
	v_mbcnt_lo_u32_b32 v1, s6, 0
	v_mbcnt_hi_u32_b32 v1, s7, v1
	v_cmp_eq_u32_e32 vcc, 0, v1
	s_getreg_b32 s3, hwreg(HW_REG_XCC_ID, 0, 4)
	s_and_b64 s[8:9], exec, vcc
	s_mov_b64 exec, s[8:9]
	s_cbranch_execz .LBB0_3
	s_load_dwordx2 s[8:9], s[0:1], 0x98
	s_lshl_b32 s3, s3, 8
	s_and_b32 s3, s3, 0xf00
	v_mov_b32_e32 v1, 0x4000
	s_waitcnt lgkmcnt(0)
	s_add_u32 s8, s8, s3
	s_addc_u32 s9, s9, 0
	s_bcnt1_i32_b64 s3, s[6:7]
	v_mov_b32_e32 v2, s3
	global_atomic_add v3, v1, v2, s[8:9] offset:1024 sc0
	s_waitcnt vmcnt(0)
	v_readfirstlane_b32 s6, v3
	s_getreg_b32 s7, hwreg(HW_REG_XCC_ID, 0, 4)
	s_and_b32 s7, s7, 7
	s_nop 0
	s_bfe_u32 s3, s6, 0x10002
	s_and_b32 s9, s6, 3
	s_lshl_b32 s9, s9, 1
	s_or_b32 s3, s3, s9
	s_lshl_b32 s9, s7, 3
	s_or_b32 s3, s3, s9
	s_lshr_b32 s9, s6, 3
	s_lshl_b32 s9, s9, 6
	s_or_b32 s3, s3, s9
	v_mov_b32_e32 v1, 0x23f08
	v_mov_b32_e32 v2, s3
	ds_write_b32 v1, v2
.LBB0_3:
	s_or_b64 exec, exec, s[4:5]
	s_waitcnt lgkmcnt(0)
	s_barrier
	v_mov_b32_e32 v1, 0x23f08
	ds_read_b32 v1, v1
	s_waitcnt lgkmcnt(0)
	v_readfirstlane_b32 s8, v1
	s_nop 1
	v_writelane_b32 v255, s8, 0
	s_load_dwordx8 s[12:19], s[0:1], 0x10
	s_load_dwordx4 s[4:7], s[0:1], 0x30
	s_load_dwordx8 s[20:27], s[0:1], 0x50
	s_load_dwordx2 s[36:37], s[0:1], 0x80
	s_load_dwordx2 s[34:35], s[0:1], 0x98
	v_mov_b32_e32 v66, v147
	v_mov_b32_e32 v1, v147
	s_movk_i32 s8, 0x1400
	s_nop 0
	v_readfirstlane_b32 s3, v66
	v_readfirstlane_b32 s33, v1
	v_cmp_gt_i32_e32 vcc, s8, v1
	v_lshl_add_u32 v26, v1, 2, 0
	s_and_saveexec_b64 s[8:9], vcc
	s_cbranch_execz .LBB0_10
	s_mov_b64 s[30:31], 0
	s_movk_i32 s40, 0x3ff
	s_movk_i32 s41, 0xfc00
	v_mov_b32_e32 v3, 0
	s_movk_i32 s42, 0x11ff
	v_mov_b32_e32 v6, v26
	v_mov_b32_e32 v7, v1
	s_branch .LBB0_6
